# LN2 and post-phase row loops: row-invariant vectors (post_g/post_b, lnx_g/lnx_b) loaded once per wave; one load round per row with counted waits
# speedup vs baseline: 1.0117x; 1.0042x over previous
.LBB0_1402:
	s_or_b64 exec, exec, s[20:21]
	s_load_dword s3, s[0:1], 0x108
	v_cmp_lt_i32_e32 vcc, 11, v10
	s_waitcnt lgkmcnt(0)
	s_cmp_lt_i32 s3, 13
	s_cselect_b64 s[6:7], -1, 0
	s_and_b64 s[6:7], s[6:7], vcc
	s_and_saveexec_b64 s[8:9], s[6:7]
	s_cbranch_execz .LBB0_1462
	s_load_dword s3, s[0:1], 0x640
	v_lshl_add_u32 v0, s2, 2, v206
	s_add_u32 s12, s0, 0x640
	s_movk_i32 s6, 0x4000
	s_addc_u32 s13, s1, 0
	v_cmp_gt_i32_e32 vcc, s6, v0
	s_and_saveexec_b64 s[10:11], vcc
	s_cbranch_execz .LBB0_1407
	v_mbcnt_lo_u32_b32 v1, -1, 0
	v_mbcnt_hi_u32_b32 v1, -1, v1
	v_and_b32_e32 v3, 64, v1
	v_xor_b32_e32 v2, 1, v1
	v_add_u32_e32 v3, 64, v3
	v_cmp_lt_i32_e32 vcc, v2, v3
	s_load_dwordx4 s[28:31], s[0:1], 0xe0
	s_load_dwordx2 s[16:17], s[0:1], 0x100
	v_cndmask_b32_e32 v2, v1, v2, vcc
	v_lshlrev_b32_e32 v13, 2, v2
	v_xor_b32_e32 v2, 2, v1
	v_cmp_lt_i32_e32 vcc, v2, v3
	v_and_b32_e32 v12, 63, v176
	s_waitcnt lgkmcnt(0)
	s_lshl_b32 s14, s3, 2
	v_cndmask_b32_e32 v1, v1, v2, vcc
	v_lshlrev_b32_e32 v14, 2, v1
	v_ashrrev_i32_e32 v1, 31, v0
	v_lshlrev_b32_e32 v10, 6, v12
	v_mov_b32_e32 v11, 0
	v_lshlrev_b64 v[6:7], 6, v[0:1]
	v_lshlrev_b64 v[8:9], 12, v[0:1]
	v_lshl_add_u64 v[2:3], s[28:29], 0, v[10:11]
	v_lshl_add_u64 v[4:5], s[30:31], 0, v[10:11]
	v_and_or_b32 v6, v176, 60, v6
	s_mov_b64 s[6:7], 0x100000
	s_ashr_i32 s15, s14, 31
	v_or_b32_e32 v8, v8, v10
	v_lshlrev_b64 v[10:11], 11, v[0:1]
	v_lshl_add_u64 v[6:7], v[6:7], 0, s[6:7]
	s_lshl_b64 s[18:19], s[14:15], 6
	s_lshl_b64 s[20:21], s[14:15], 12
	v_lshl_or_b32 v10, v12, 5, v10
	s_lshl_b64 s[28:29], s[14:15], 11
	s_mov_b64 s[26:27], 0
	s_mov_b64 s[30:31], 0xa200000
	s_mov_b64 s[34:35], 0x6200000
	s_mov_b64 s[36:37], 0x8200000
	s_mov_b32 s15, 0xa200000
	v_mov_b32_e32 v1, 0x3a27c5ac
	s_mov_b32 s38, 0x800000
	s_mov_b32 s39, 0x200000
	s_movk_i32 s40, 0x3fff
	global_load_dwordx4 v[88:91], v[2:3], off offset:16
	global_load_dwordx4 v[92:95], v[2:3], off
	global_load_dwordx4 v[96:99], v[2:3], off offset:48
	global_load_dwordx4 v[100:103], v[2:3], off offset:32
	global_load_dwordx4 v[104:107], v[4:5], off offset:16
	global_load_dwordx4 v[108:111], v[4:5], off
	global_load_dwordx4 v[112:115], v[4:5], off offset:48
	global_load_dwordx4 v[116:119], v[4:5], off offset:32
.LBB0_1405:
	v_lshl_add_u64 v[32:33], s[16:17], 0, v[8:9]
	v_lshl_add_u64 v[34:35], s[16:17], 0, v[6:7]
	v_lshl_add_u64 v[56:57], s[16:17], 0, v[10:11]
	v_add_co_u32_e64 v64, s[6:7], s15, v32
	global_load_dword v12, v[34:35], off
	v_lshl_add_u64 v[34:35], v[56:57], 0, s[34:35]
	v_add_co_u32_e32 v62, vcc, 0x6200000, v56
	v_addc_co_u32_e64 v65, s[6:7], 0, v33, s[6:7]
	v_lshl_add_u64 v[58:59], v[32:33], 0, s[30:31]
	v_addc_co_u32_e32 v63, vcc, 0, v57, vcc
	global_load_dwordx4 v[32:35], v[34:35], off offset:16
	s_nop 0
	global_load_dwordx4 v[36:39], v[64:65], off
	global_load_dwordx4 v[40:43], v[58:59], off offset:48
	global_load_dwordx4 v[44:47], v[58:59], off offset:32
	global_load_dwordx4 v[48:51], v[58:59], off offset:16
	global_load_dwordx4 v[52:55], v[62:63], off
	v_lshl_add_u64 v[60:61], v[56:57], 0, s[36:37]
	v_add_co_u32_e64 v66, s[6:7], s39, v56
	v_add_co_u32_e32 v56, vcc, 0x8200000, v56
	s_nop 0
	v_addc_co_u32_e64 v67, s[6:7], 0, v57, s[6:7]
	v_addc_co_u32_e32 v57, vcc, 0, v57, vcc
	global_load_dwordx4 v[56:59], v[56:57], off
	global_load_dwordx4 v[120:123], v[60:61], off offset:16
	v_add_u32_e32 v0, s14, v0
	v_lshl_add_u64 v[6:7], v[6:7], 0, s[18:19]
	v_lshl_add_u64 v[8:9], v[8:9], 0, s[20:21]
	v_lshl_add_u64 v[10:11], v[10:11], 0, s[28:29]
	s_waitcnt vmcnt(6)
	v_add_f32_e32 v15, 0, v36
	v_add_f32_e32 v15, v15, v37
	v_add_f32_e32 v15, v15, v38
	v_add_f32_e32 v15, v15, v39
	s_waitcnt vmcnt(3)
	v_add_f32_e32 v15, v15, v48
	v_add_f32_e32 v15, v15, v49
	v_add_f32_e32 v15, v15, v50
	v_add_f32_e32 v15, v15, v51
	v_add_f32_e32 v15, v15, v44
	v_add_f32_e32 v15, v15, v45
	v_add_f32_e32 v15, v15, v46
	v_add_f32_e32 v15, v15, v47
	v_add_f32_e32 v15, v15, v40
	v_add_f32_e32 v15, v15, v41
	v_add_f32_e32 v15, v15, v42
	v_add_f32_e32 v15, v15, v43
	ds_bpermute_b32 v72, v13, v15
	s_waitcnt vmcnt(2)
	v_lshlrev_b32_e32 v62, 16, v52
	v_and_b32_e32 v63, 0xffff0000, v52
	v_lshlrev_b32_e32 v52, 16, v53
	v_and_b32_e32 v53, 0xffff0000, v53
	s_waitcnt lgkmcnt(0)
	v_add_f32_e32 v15, v15, v72
	ds_bpermute_b32 v72, v14, v15
	v_lshlrev_b32_e32 v64, 16, v54
	v_and_b32_e32 v65, 0xffff0000, v54
	v_lshlrev_b32_e32 v54, 16, v55
	v_and_b32_e32 v55, 0xffff0000, v55
	s_waitcnt lgkmcnt(0)
	v_add_f32_e32 v15, v15, v72
	v_mul_f32_e32 v72, 0x3c800000, v15
	v_pk_add_f32 v[36:37], v[36:37], v[72:73] op_sel_hi:[1,0] neg_lo:[0,1] neg_hi:[0,1]
	v_pk_add_f32 v[38:39], v[38:39], v[72:73] op_sel_hi:[1,0] neg_lo:[0,1] neg_hi:[0,1]
	v_pk_add_f32 v[48:49], v[48:49], v[72:73] op_sel_hi:[1,0] neg_lo:[0,1] neg_hi:[0,1]
	v_pk_add_f32 v[50:51], v[50:51], v[72:73] op_sel_hi:[1,0] neg_lo:[0,1] neg_hi:[0,1]
	v_pk_add_f32 v[44:45], v[44:45], v[72:73] op_sel_hi:[1,0] neg_lo:[0,1] neg_hi:[0,1]
	v_pk_add_f32 v[46:47], v[46:47], v[72:73] op_sel_hi:[1,0] neg_lo:[0,1] neg_hi:[0,1]
	v_pk_add_f32 v[40:41], v[40:41], v[72:73] op_sel_hi:[1,0] neg_lo:[0,1] neg_hi:[0,1]
	v_pk_add_f32 v[42:43], v[42:43], v[72:73] op_sel_hi:[1,0] neg_lo:[0,1] neg_hi:[0,1]
	v_pk_mul_f32 v[72:73], v[36:37], v[36:37]
	v_pk_mul_f32 v[74:75], v[38:39], v[38:39]
	v_add_f32_e32 v15, v72, v73
	v_add_f32_e32 v15, v74, v15
	v_pk_mul_f32 v[76:77], v[48:49], v[48:49]
	v_add_f32_e32 v15, v75, v15
	v_add_f32_e32 v15, v76, v15
	v_pk_mul_f32 v[78:79], v[50:51], v[50:51]
	v_add_f32_e32 v15, v77, v15
	v_add_f32_e32 v15, v78, v15
	v_pk_mul_f32 v[80:81], v[44:45], v[44:45]
	v_add_f32_e32 v15, v79, v15
	v_add_f32_e32 v15, v80, v15
	v_pk_mul_f32 v[82:83], v[46:47], v[46:47]
	v_add_f32_e32 v15, v81, v15
	v_add_f32_e32 v15, v82, v15
	v_pk_mul_f32 v[84:85], v[40:41], v[40:41]
	v_add_f32_e32 v15, v83, v15
	v_add_f32_e32 v15, v84, v15
	v_pk_mul_f32 v[86:87], v[42:43], v[42:43]
	v_add_f32_e32 v15, v85, v15
	v_add_f32_e32 v15, v86, v15
	v_add_f32_e32 v15, v87, v15
	ds_bpermute_b32 v72, v13, v15
	s_waitcnt vmcnt(1)
	v_lshlrev_b32_e32 v68, 16, v56
	v_and_b32_e32 v69, 0xffff0000, v56
	v_lshlrev_b32_e32 v56, 16, v57
	v_and_b32_e32 v57, 0xffff0000, v57
	s_waitcnt lgkmcnt(0)
	v_add_f32_e32 v15, v15, v72
	ds_bpermute_b32 v72, v14, v15
	v_lshlrev_b32_e32 v70, 16, v58
	v_and_b32_e32 v71, 0xffff0000, v58
	v_lshlrev_b32_e32 v58, 16, v59
	v_and_b32_e32 v59, 0xffff0000, v59
	s_waitcnt lgkmcnt(0)
	v_add_f32_e32 v15, v15, v72
	v_fmamk_f32 v15, v15, 0x3c800000, v1
	v_mul_f32_e32 v72, 0x4b800000, v15
	v_cmp_gt_f32_e32 vcc, s38, v15
	s_nop 1
	v_cndmask_b32_e32 v15, v15, v72, vcc
	v_rsq_f32_e32 v15, v15
	s_nop 0
	v_mul_f32_e32 v72, 0x45800000, v15
	v_cndmask_b32_e32 v72, v15, v72, vcc
	v_pk_mul_f32 v[36:37], v[36:37], v[72:73] op_sel_hi:[1,0]
	v_pk_mul_f32 v[38:39], v[38:39], v[72:73] op_sel_hi:[1,0]
	v_pk_mul_f32 v[48:49], v[48:49], v[72:73] op_sel_hi:[1,0]
	v_pk_mul_f32 v[50:51], v[50:51], v[72:73] op_sel_hi:[1,0]
	v_pk_fma_f32 v[20:21], v[92:93], v[36:37], v[108:109]
	v_pk_fma_f32 v[22:23], v[94:95], v[38:39], v[110:111]
	v_pk_fma_f32 v[16:17], v[88:89], v[48:49], v[104:105]
	v_pk_fma_f32 v[18:19], v[90:91], v[50:51], v[106:107]
	v_pk_fma_f32 v[20:21], v[12:13], v[62:63], v[20:21] op_sel_hi:[0,1,1]
	v_pk_fma_f32 v[22:23], v[12:13], v[52:53], v[22:23] op_sel_hi:[0,1,1]
	v_pk_fma_f32 v[16:17], v[12:13], v[64:65], v[16:17] op_sel_hi:[0,1,1]
	v_pk_fma_f32 v[18:19], v[12:13], v[54:55], v[18:19] op_sel_hi:[0,1,1]
	v_pk_mul_f32 v[20:21], v[20:21], v[68:69]
	v_pk_mul_f32 v[22:23], v[22:23], v[56:57]
	v_pk_mul_f32 v[24:25], v[16:17], v[70:71]
	v_pk_mul_f32 v[26:27], v[18:19], v[58:59]
	v_cvt_pk_bf16_f32 v16, v20, v21
	v_cvt_pk_bf16_f32 v17, v22, v23
	v_cvt_pk_bf16_f32 v18, v24, v25
	v_cvt_pk_bf16_f32 v19, v26, v27
	global_store_dwordx4 v[66:67], v[16:19], off
	v_pk_mul_f32 v[44:45], v[44:45], v[72:73] op_sel_hi:[1,0]
	v_pk_mul_f32 v[46:47], v[46:47], v[72:73] op_sel_hi:[1,0]
	v_pk_mul_f32 v[40:41], v[40:41], v[72:73] op_sel_hi:[1,0]
	v_pk_mul_f32 v[42:43], v[42:43], v[72:73] op_sel_hi:[1,0]
	v_lshlrev_b32_e32 v48, 16, v32
	v_and_b32_e32 v49, 0xffff0000, v32
	v_lshlrev_b32_e32 v32, 16, v33
	v_and_b32_e32 v33, 0xffff0000, v33
	v_lshlrev_b32_e32 v52, 16, v34
	v_and_b32_e32 v53, 0xffff0000, v34
	v_lshlrev_b32_e32 v34, 16, v35
	v_and_b32_e32 v35, 0xffff0000, v35
	v_cmp_lt_i32_e32 vcc, s40, v0
	s_or_b64 s[26:27], vcc, s[26:27]
	v_pk_fma_f32 v[16:17], v[40:41], v[96:97], v[112:113]
	v_pk_fma_f32 v[20:21], v[44:45], v[100:101], v[116:117]
	v_pk_fma_f32 v[22:23], v[46:47], v[102:103], v[118:119]
	v_pk_fma_f32 v[18:19], v[42:43], v[98:99], v[114:115]
	s_waitcnt vmcnt(1)
	v_lshlrev_b32_e32 v50, 16, v120
	v_and_b32_e32 v51, 0xffff0000, v120
	v_lshlrev_b32_e32 v36, 16, v121
	v_and_b32_e32 v37, 0xffff0000, v121
	v_lshlrev_b32_e32 v54, 16, v122
	v_and_b32_e32 v55, 0xffff0000, v122
	v_lshlrev_b32_e32 v38, 16, v123
	v_and_b32_e32 v39, 0xffff0000, v123
	v_pk_fma_f32 v[20:21], v[12:13], v[48:49], v[20:21] op_sel_hi:[0,1,1]
	v_pk_fma_f32 v[22:23], v[12:13], v[32:33], v[22:23] op_sel_hi:[0,1,1]
	v_pk_fma_f32 v[16:17], v[12:13], v[52:53], v[16:17] op_sel_hi:[0,1,1]
	v_pk_fma_f32 v[18:19], v[12:13], v[34:35], v[18:19] op_sel_hi:[0,1,1]
	v_pk_mul_f32 v[20:21], v[20:21], v[50:51]
	v_pk_mul_f32 v[22:23], v[22:23], v[36:37]
	v_pk_mul_f32 v[24:25], v[16:17], v[54:55]
	v_pk_mul_f32 v[26:27], v[18:19], v[38:39]
	v_cvt_pk_bf16_f32 v16, v20, v21
	v_cvt_pk_bf16_f32 v17, v22, v23
	v_cvt_pk_bf16_f32 v18, v24, v25
	v_cvt_pk_bf16_f32 v19, v26, v27
	global_store_dwordx4 v[66:67], v[16:19], off offset:16
	s_andn2_b64 exec, exec, s[26:27]
	s_cbranch_execnz .LBB0_1405
	s_or_b64 exec, exec, s[26:27]
	s_load_dword s6, s[0:1], 0x10c
	s_waitcnt lgkmcnt(0)
	v_mov_b32_e32 v10, s6

.LBB0_1524:
	s_or_b64 exec, exec, s[6:7]
	s_load_dword s3, s[0:1], 0x108
	v_cmp_lt_i32_e32 vcc, 13, v10
	s_waitcnt lgkmcnt(0)
	s_cmp_lt_i32 s3, 15
	s_cselect_b64 s[6:7], -1, 0
	s_and_b64 s[6:7], s[6:7], vcc
	s_and_saveexec_b64 s[8:9], s[6:7]
	s_cbranch_execz .LBB0_1585
	s_load_dword s30, s[0:1], 0x640
	v_lshl_add_u32 v0, s2, 2, v206
	s_add_u32 s6, s0, 0x640
	s_movk_i32 s31, 0x4000
	s_addc_u32 s7, s1, 0
	v_cmp_gt_i32_e32 vcc, s31, v0
	s_and_saveexec_b64 s[16:17], vcc
	s_cbranch_execz .LBB0_1531
	s_load_dwordx4 s[8:11], s[0:1], 0xf8
	v_ashrrev_i32_e32 v1, 31, v0
	v_lshlrev_b32_e32 v4, 2, v176
	v_lshlrev_b64 v[2:3], 11, v[0:1]
	v_and_b32_e32 v8, 0xfc, v4
	s_waitcnt lgkmcnt(0)
	v_lshl_add_u64 v[2:3], s[10:11], 0, v[2:3]
	v_lshlrev_b32_e32 v6, 1, v8
	v_mov_b32_e32 v7, 0
	v_lshl_add_u64 v[2:3], v[2:3], 0, v[6:7]
	s_mov_b64 s[2:3], 0x2200000
	s_mov_b32 s18, 0x2200000
	v_lshl_add_u64 v[4:5], v[2:3], 0, s[2:3]
	v_add_co_u32_e32 v2, vcc, s18, v2
	s_load_dwordx4 s[12:15], s[0:1], 0x48
	s_nop 0
	v_addc_co_u32_e32 v3, vcc, 0, v3, vcc
	global_load_dwordx2 v[18:19], v[4:5], off offset:1536
	global_load_dwordx2 v[20:21], v[4:5], off offset:1024
	global_load_dwordx2 v[22:23], v[4:5], off offset:512
	global_load_dwordx2 v[24:25], v[2:3], off
	v_mbcnt_lo_u32_b32 v2, -1, 0
	v_mbcnt_hi_u32_b32 v9, -1, v2
	s_lshl_b32 s18, s30, 2
	v_and_b32_e32 v10, 64, v9
	v_lshlrev_b64 v[2:3], 12, v[0:1]
	v_add_u32_e32 v4, s18, v0
	v_xor_b32_e32 v1, 16, v9
	v_add_u32_e32 v10, 64, v10
	v_xor_b32_e32 v11, 32, v9
	v_ashrrev_i32_e32 v5, 31, v4
	v_cmp_lt_i32_e32 vcc, v1, v10
	v_and_b32_e32 v6, 63, v176
	v_lshlrev_b64 v[4:5], 11, v[4:5]
	v_cndmask_b32_e32 v1, v9, v1, vcc
	v_cmp_lt_i32_e32 vcc, v11, v10
	v_lshl_or_b32 v2, v6, 4, v2
	v_lshl_or_b32 v4, v6, 3, v4
	v_cndmask_b32_e32 v9, v9, v11, vcc
	v_lshlrev_b32_e32 v6, 2, v8
	s_mov_b64 s[36:37], 0x1000
	s_ashr_i32 s19, s18, 31
	v_lshlrev_b32_e32 v27, 2, v9
	v_lshl_add_u64 v[4:5], s[10:11], 0, v[4:5]
	s_waitcnt lgkmcnt(0)
	v_lshl_add_u64 v[8:9], s[12:13], 0, v[6:7]
	v_lshl_add_u64 v[10:11], s[14:15], 0, v[6:7]
	s_mov_b64 s[20:21], 0
	s_movk_i32 s34, 0x3fff
	v_mov_b32_e32 v26, 0x358637bd
	s_mov_b32 s35, 0x800000
	s_lshl_b64 s[26:27], s[18:19], 12
	s_lshl_b64 s[28:29], s[18:19], 11
	v_lshlrev_b32_e32 v1, 2, v1
	v_lshl_add_u64 v[2:3], s[8:9], 0, v[2:3]
	v_lshl_add_u64 v[4:5], v[4:5], 0, s[2:3]
	v_lshl_add_u64 v[6:7], v[8:9], 0, s[36:37]
	v_lshl_add_u64 v[8:9], v[10:11], 0, s[36:37]
	s_waitcnt vmcnt(3)
	v_mov_b64_e32 v[10:11], v[18:19]
	s_waitcnt vmcnt(2)
	v_mov_b64_e32 v[12:13], v[20:21]
	s_waitcnt vmcnt(1)
	v_mov_b64_e32 v[14:15], v[22:23]
	s_waitcnt vmcnt(0)
	v_mov_b64_e32 v[16:17], v[24:25]
	global_load_dwordx4 v[84:87], v[6:7], off
	global_load_dwordx4 v[88:91], v[8:9], off
	global_load_dwordx4 v[92:95], v[6:7], off offset:1024
	global_load_dwordx4 v[96:99], v[8:9], off offset:1024
	global_load_dwordx4 v[100:103], v[6:7], off offset:2048
	global_load_dwordx4 v[104:107], v[8:9], off offset:2048
	global_load_dwordx4 v[108:111], v[6:7], off offset:3072
	global_load_dwordx4 v[112:115], v[8:9], off offset:3072
	s_branch .LBB0_1528
.LBB0_1527:
	s_or_b64 exec, exec, s[8:9]
	v_lshlrev_b32_e32 v28, 16, v24
	v_and_b32_e32 v29, 0xffff0000, v24
	v_lshlrev_b32_e32 v32, 16, v22
	v_and_b32_e32 v33, 0xffff0000, v22
	v_lshlrev_b32_e32 v30, 16, v25
	v_lshlrev_b32_e32 v34, 16, v23
	v_lshlrev_b32_e32 v36, 16, v20
	v_and_b32_e32 v37, 0xffff0000, v20
	v_lshlrev_b32_e32 v38, 16, v21
	v_and_b32_e32 v39, 0xffff0000, v21
	v_lshlrev_b32_e32 v40, 16, v18
	v_and_b32_e32 v41, 0xffff0000, v18
	v_lshlrev_b32_e32 v42, 16, v19
	v_and_b32_e32 v43, 0xffff0000, v19
	v_mov_b32_e32 v18, v32
	v_mov_b32_e32 v19, v28
	v_mov_b32_e32 v20, v33
	v_mov_b32_e32 v21, v29
	v_and_b32_e32 v31, 0xffff0000, v25
	v_and_b32_e32 v35, 0xffff0000, v23
	v_pk_add_f32 v[18:19], v[18:19], v[20:21]
	v_mov_b32_e32 v20, v34
	v_mov_b32_e32 v21, v30
	v_pk_add_f32 v[18:19], v[18:19], v[20:21]
	v_mov_b32_e32 v20, v35
	v_mov_b32_e32 v21, v31
	v_pk_add_f32 v[18:19], v[18:19], v[20:21]
	v_mov_b32_e32 v20, v41
	v_add_f32_e32 v19, 0, v19
	v_add_f32_e32 v22, v18, v19
	v_mov_b32_e32 v18, v40
	v_mov_b32_e32 v19, v36
	v_mov_b32_e32 v21, v37
	v_pk_add_f32 v[18:19], v[18:19], v[20:21]
	v_mov_b32_e32 v20, v42
	v_mov_b32_e32 v21, v38
	v_pk_add_f32 v[18:19], v[18:19], v[20:21]
	v_mov_b32_e32 v20, v43
	v_mov_b32_e32 v21, v39
	v_pk_add_f32 v[18:19], v[18:19], v[20:21]
	v_lshl_add_u64 v[4:5], v[4:5], 0, s[28:29]
	v_add_f32_e32 v19, v19, v22
	v_add_f32_e32 v44, v18, v19
	s_nop 1
	v_add_f32_dpp v44, v44, v44 quad_perm:[1,0,3,2] row_mask:0xf bank_mask:0xf bound_ctrl:1
	s_nop 1
	v_add_f32_dpp v44, v44, v44 quad_perm:[2,3,0,1] row_mask:0xf bank_mask:0xf bound_ctrl:1
	s_nop 1
	v_add_f32_dpp v44, v44, v44 row_half_mirror row_mask:0xf bank_mask:0xf bound_ctrl:1
	s_nop 1
	v_add_f32_dpp v44, v44, v44 row_mirror row_mask:0xf bank_mask:0xf bound_ctrl:1
	ds_bpermute_b32 v45, v1, v44
	s_waitcnt lgkmcnt(0)
	v_add_f32_e32 v44, v44, v45
	ds_bpermute_b32 v45, v27, v44
	s_waitcnt lgkmcnt(0)
	v_add_f32_e32 v44, v44, v45
	v_mul_f32_e32 v44, 0x3a800000, v44
	v_pk_add_f32 v[28:29], v[28:29], v[44:45] op_sel_hi:[1,0] neg_lo:[0,1] neg_hi:[0,1]
	v_pk_add_f32 v[32:33], v[32:33], v[44:45] op_sel_hi:[1,0] neg_lo:[0,1] neg_hi:[0,1]
	v_mov_b32_e32 v48, v29
	v_mov_b32_e32 v49, v33
	v_pk_add_f32 v[30:31], v[30:31], v[44:45] op_sel_hi:[1,0] neg_lo:[0,1] neg_hi:[0,1]
	v_pk_add_f32 v[34:35], v[34:35], v[44:45] op_sel_hi:[1,0] neg_lo:[0,1] neg_hi:[0,1]
	v_mov_b32_e32 v46, v28
	v_mov_b32_e32 v47, v32
	v_pk_mul_f32 v[48:49], v[48:49], v[48:49]
	v_pk_add_f32 v[36:37], v[36:37], v[44:45] op_sel_hi:[1,0] neg_lo:[0,1] neg_hi:[0,1]
	v_pk_fma_f32 v[46:47], v[46:47], v[46:47], v[48:49]
	v_mov_b32_e32 v48, v30
	v_mov_b32_e32 v49, v34
	v_pk_add_f32 v[40:41], v[40:41], v[44:45] op_sel_hi:[1,0] neg_lo:[0,1] neg_hi:[0,1]
	v_pk_fma_f32 v[46:47], v[48:49], v[48:49], v[46:47]
	v_mov_b32_e32 v48, v41
	v_mov_b32_e32 v49, v37
	v_pk_add_f32 v[38:39], v[38:39], v[44:45] op_sel_hi:[1,0] neg_lo:[0,1] neg_hi:[0,1]
	v_pk_add_f32 v[42:43], v[42:43], v[44:45] op_sel_hi:[1,0] neg_lo:[0,1] neg_hi:[0,1]
	v_mov_b32_e32 v44, v40
	v_mov_b32_e32 v45, v36
	v_pk_mul_f32 v[48:49], v[48:49], v[48:49]
	v_mov_b32_e32 v50, v31
	v_mov_b32_e32 v51, v35
	v_pk_fma_f32 v[44:45], v[44:45], v[44:45], v[48:49]
	v_mov_b32_e32 v48, v42
	v_mov_b32_e32 v49, v38
	v_pk_fma_f32 v[46:47], v[50:51], v[50:51], v[46:47]
	v_mov_b32_e32 v50, v43
	v_mov_b32_e32 v51, v39
	v_pk_fma_f32 v[44:45], v[48:49], v[48:49], v[44:45]
	v_add_f32_e32 v46, v46, v47
	v_pk_fma_f32 v[44:45], v[50:51], v[50:51], v[44:45]
	s_nop 0
	v_add_f32_e32 v45, v45, v46
	v_add_f32_e32 v44, v44, v45
	s_nop 1
	v_add_f32_dpp v44, v44, v44 quad_perm:[1,0,3,2] row_mask:0xf bank_mask:0xf bound_ctrl:1
	s_nop 1
	v_add_f32_dpp v44, v44, v44 quad_perm:[2,3,0,1] row_mask:0xf bank_mask:0xf bound_ctrl:1
	s_nop 1
	v_add_f32_dpp v44, v44, v44 row_half_mirror row_mask:0xf bank_mask:0xf bound_ctrl:1
	s_nop 1
	v_add_f32_dpp v44, v44, v44 row_mirror row_mask:0xf bank_mask:0xf bound_ctrl:1
	ds_bpermute_b32 v45, v1, v44
	s_waitcnt lgkmcnt(0)
	v_add_f32_e32 v44, v44, v45
	ds_bpermute_b32 v45, v27, v44
	s_waitcnt lgkmcnt(0)
	v_add_f32_e32 v44, v44, v45
	v_fmamk_f32 v44, v44, 0x3a800000, v26
	v_mul_f32_e32 v45, 0x4b800000, v44
	v_cmp_gt_f32_e64 s[2:3], s35, v44
	s_nop 1
	v_cndmask_b32_e64 v44, v44, v45, s[2:3]
	v_rsq_f32_e32 v44, v44
	s_nop 0
	v_mul_f32_e32 v45, 0x45800000, v44
	v_cndmask_b32_e64 v44, v44, v45, s[2:3]
	v_pk_mul_f32 v[28:29], v[28:29], v[44:45] op_sel_hi:[1,0]
	s_and_b64 s[2:3], exec, vcc
	s_cmp_eq_u64 s[60:61], 0
	s_cbranch_scc1 .Lln2_w0
	s_waitcnt vmcnt(4)
	s_branch .Lln2_w1

.Lln2_w1:
	v_pk_fma_f32 v[18:19], v[84:85], v[28:29], v[88:89]
	v_pk_mul_f32 v[22:23], v[30:31], v[44:45] op_sel_hi:[1,0]
	v_pk_mul_f32 v[28:29], v[32:33], v[44:45] op_sel_hi:[1,0]
	v_pk_fma_f32 v[20:21], v[86:87], v[22:23], v[90:91]
	global_store_dwordx4 v[2:3], v[18:21], off
	v_pk_mul_f32 v[30:31], v[34:35], v[44:45] op_sel_hi:[1,0]
	s_or_b64 s[20:21], s[2:3], s[20:21]
	s_nop 0
	v_pk_fma_f32 v[18:19], v[92:93], v[28:29], v[96:97]
	v_pk_fma_f32 v[20:21], v[94:95], v[30:31], v[98:99]
	global_store_dwordx4 v[2:3], v[18:21], off offset:1024
	v_pk_mul_f32 v[28:29], v[36:37], v[44:45] op_sel_hi:[1,0]
	v_pk_mul_f32 v[30:31], v[38:39], v[44:45] op_sel_hi:[1,0]
	v_pk_mul_f32 v[36:37], v[42:43], v[44:45] op_sel_hi:[1,0]
	v_pk_fma_f32 v[18:19], v[28:29], v[100:101], v[104:105]
	v_pk_fma_f32 v[20:21], v[30:31], v[102:103], v[106:107]
	global_store_dwordx4 v[2:3], v[18:21], off offset:2048
	v_pk_mul_f32 v[24:25], v[40:41], v[44:45] op_sel_hi:[1,0]
	s_waitcnt vmcnt(3)
	s_nop 0
	v_mov_b64_e32 v[18:19], v[10:11]
	v_mov_b64_e32 v[20:21], v[12:13]
	v_mov_b64_e32 v[22:23], v[14:15]
	v_pk_fma_f32 v[28:29], v[24:25], v[108:109], v[112:113]
	v_pk_fma_f32 v[30:31], v[36:37], v[110:111], v[114:115]
	global_store_dwordx4 v[2:3], v[28:31], off offset:3072
	v_lshl_add_u64 v[2:3], v[2:3], 0, s[26:27]
	v_mov_b64_e32 v[24:25], v[16:17]
	s_andn2_b64 exec, exec, s[20:21]
	s_cbranch_execz .LBB0_1530
.LBB0_1528:
	v_add_u32_e32 v0, s18, v0
	v_cmp_gt_i32_e64 s[2:3], s31, v0
	s_mov_b64 s[60:61], s[2:3]
	v_cmp_lt_i32_e32 vcc, s34, v0
	s_and_saveexec_b64 s[8:9], s[2:3]
	s_cbranch_execz .LBB0_1527
	global_load_dwordx2 v[16:17], v[4:5], off
	global_load_dwordx2 v[14:15], v[4:5], off offset:512
	global_load_dwordx2 v[12:13], v[4:5], off offset:1024
	global_load_dwordx2 v[10:11], v[4:5], off offset:1536
	s_branch .LBB0_1527
